# MoBA packed tiles: per-block K/V chunk addresses computed only by the wave that processes a pair of that block (was every wave for every block)
# speedup vs baseline: 1.0001x; 1.0001x over previous
.LBB0_1911:
	s_lshl_b32 s18, s74, 5
	s_add_i32 s18, s18, 0
	s_add_i32 s18, s18, 0x23000
	v_mov_b32_e32 v1, s18
	ds_read_b32 v2, v1
	s_waitcnt lgkmcnt(1)
	ds_read_b32 v3, v1 offset:4
	ds_read_b32 v4, v1 offset:8
	ds_read_b32 v5, v1 offset:12
	ds_read_b32 v6, v1 offset:16
	s_waitcnt lgkmcnt(3)
	v_add_u32_e32 v2, v3, v2
	s_waitcnt lgkmcnt(2)
	v_add_u32_e32 v2, v2, v4
	ds_read_b32 v3, v1 offset:20
	ds_read_b32 v4, v1 offset:24
	ds_read_b32 v1, v1 offset:28
	s_waitcnt lgkmcnt(4)
	v_add_u32_e32 v2, v2, v5
	s_waitcnt lgkmcnt(3)
	v_add_u32_e32 v2, v2, v6
	s_waitcnt lgkmcnt(2)
	v_add_u32_e32 v2, v2, v3
	s_waitcnt lgkmcnt(1)
	v_add_u32_e32 v2, v2, v4
	s_waitcnt lgkmcnt(0)
	v_add_u32_e32 v1, v2, v1
	s_nop 0
	v_readfirstlane_b32 s75, v1
	s_add_i32 s18, s75, 31
	s_ashr_i32 s77, s18, 5
	s_add_i32 s18, s77, 1
	s_ashr_i32 s76, s18, 1
	s_cmp_lt_i32 s76, 1
	s_cbranch_scc1 .LBB0_1910
	s_lshl_b32 s18, s29, 2
	s_add_i32 s78, s18, 0
	s_add_i32 s77, s77, -1
	s_add_i32 s78, s78, 0x23200
	s_mov_b32 s79, 0
	s_branch .LBB0_1915

.LBB0_1915:
	s_add_i32 s18, s79, s28
	s_and_b32 s18, s18, 7
	s_cmp_lg_u32 s18, s82
	s_cbranch_scc1 .LBB0_1914
	v_lshl_or_b32 v166, s74, 8, v225
	v_lshl_add_u64 v[2:3], s[72:73], 0, v[166:167]
	v_lshlrev_b64 v[2:3], 11, v[2:3]
	v_lshlrev_b32_e32 v1, 1, v184
	v_or_b32_e32 v2, v2, v1
	v_lshl_add_u64 v[190:191], s[40:41], 0, v[2:3]
	v_lshl_add_u64 v[192:193], s[42:43], 0, v[2:3]
	v_or_b32_e32 v2, 8, v166
	v_mov_b32_e32 v3, v167
	v_lshl_add_u64 v[2:3], s[72:73], 0, v[2:3]
	v_lshlrev_b64 v[2:3], 11, v[2:3]
	v_or_b32_e32 v2, v2, v1
	v_lshl_add_u64 v[194:195], s[40:41], 0, v[2:3]
	v_lshl_add_u64 v[198:199], s[42:43], 0, v[2:3]
	v_or_b32_e32 v2, 16, v166
	v_mov_b32_e32 v3, v167
	v_lshl_add_u64 v[2:3], s[72:73], 0, v[2:3]
	v_lshlrev_b64 v[2:3], 11, v[2:3]
	v_or_b32_e32 v2, v2, v1
	v_lshl_add_u64 v[200:201], s[40:41], 0, v[2:3]
	v_lshl_add_u64 v[202:203], s[42:43], 0, v[2:3]
	v_or_b32_e32 v2, 24, v166
	v_mov_b32_e32 v3, v167
	v_lshl_add_u64 v[2:3], s[72:73], 0, v[2:3]
	v_lshlrev_b64 v[2:3], 11, v[2:3]
	v_or_b32_e32 v2, v2, v1
	v_lshl_add_u64 v[204:205], s[40:41], 0, v[2:3]
	v_lshl_add_u64 v[206:207], s[42:43], 0, v[2:3]
	v_or_b32_e32 v2, 32, v166
	v_mov_b32_e32 v3, v167
	v_lshl_add_u64 v[2:3], s[72:73], 0, v[2:3]
	v_lshlrev_b64 v[2:3], 11, v[2:3]
	v_or_b32_e32 v2, v2, v1
	v_lshl_add_u64 v[208:209], s[40:41], 0, v[2:3]
	v_lshl_add_u64 v[210:211], s[42:43], 0, v[2:3]
	v_or_b32_e32 v2, 40, v166
	v_mov_b32_e32 v3, v167
	v_lshl_add_u64 v[2:3], s[72:73], 0, v[2:3]
	v_lshlrev_b64 v[2:3], 11, v[2:3]
	v_or_b32_e32 v2, v2, v1
	v_lshl_add_u64 v[212:213], s[40:41], 0, v[2:3]
	v_lshl_add_u64 v[214:215], s[42:43], 0, v[2:3]
	v_or_b32_e32 v2, 48, v166
	v_mov_b32_e32 v3, v167
	v_lshl_add_u64 v[2:3], s[72:73], 0, v[2:3]
	v_lshlrev_b64 v[2:3], 11, v[2:3]
	v_or_b32_e32 v2, v2, v1
	v_or_b32_e32 v166, 56, v166
	v_lshl_add_u64 v[216:217], s[40:41], 0, v[2:3]
	v_lshl_add_u64 v[218:219], s[42:43], 0, v[2:3]
	v_lshl_add_u64 v[2:3], s[72:73], 0, v[166:167]
	v_lshlrev_b64 v[2:3], 11, v[2:3]
	v_or_b32_e32 v2, v2, v1
	v_lshl_add_u64 v[220:221], s[40:41], 0, v[2:3]
	v_lshl_add_u64 v[222:223], s[42:43], 0, v[2:3]
	s_lshl_b32 s22, s79, 1
	s_cmp_lt_i32 s22, s77
	s_cselect_b64 s[20:21], -1, 0
	s_lshl_b32 s18, s79, 6
	s_or_b32 s23, s18, 32
	v_or_b32_e32 v1, s18, v197
	v_or_b32_e32 v2, s23, v197
	s_waitcnt lgkmcnt(0)
	v_mov_b32_e32 v3, s18
	v_cmp_gt_i32_e64 s[18:19], s75, v1
	v_mov_b32_e32 v4, s23
	v_cmp_gt_i32_e64 s[24:25], s75, v2
	v_cndmask_b32_e64 v1, v3, v1, s[18:19]
	v_lshl_add_u32 v166, v1, 2, s78
	v_cndmask_b32_e64 v2, v4, v2, s[24:25]
	v_cndmask_b32_e64 v2, v3, v2, s[20:21]
	ds_read_b32 v1, v166
	v_lshl_add_u32 v181, v2, 2, s78
	ds_read_b32 v6, v181
	v_mov_b32_e32 v3, s71
	v_add_u32_e32 v242, v231, v164
	s_waitcnt lgkmcnt(1)
	v_or_b32_sdwa v2, s70, v1 dst_sel:DWORD dst_unused:UNUSED_PAD src0_sel:DWORD src1_sel:BYTE_0
	v_lshlrev_b64 v[4:5], 11, v[2:3]
	s_waitcnt lgkmcnt(0)
	v_or_b32_sdwa v2, s70, v6 dst_sel:DWORD dst_unused:UNUSED_PAD src0_sel:DWORD src1_sel:BYTE_0
	v_lshlrev_b64 v[2:3], 11, v[2:3]
	v_lshl_add_u64 v[14:15], v[186:187], 0, v[4:5]
	v_lshl_add_u64 v[48:49], v[186:187], 0, v[2:3]
	global_load_dwordx4 v[2:5], v[14:15], off
	global_load_dwordx4 v[6:9], v[14:15], off offset:32
	global_load_dwordx4 v[10:13], v[14:15], off offset:64
	global_load_dwordx4 v[32:35], v[14:15], off offset:96
	global_load_dwordx4 v[36:39], v[48:49], off
	global_load_dwordx4 v[40:43], v[48:49], off offset:32
	global_load_dwordx4 v[44:47], v[48:49], off offset:64
	s_nop 0
	global_load_dwordx4 v[48:51], v[48:49], off offset:96
	s_nop 0
	global_load_dwordx4 v[52:55], v[190:191], off
	global_load_dwordx4 v[56:59], v[192:193], off
	global_load_dwordx4 v[60:63], v[194:195], off
	global_load_dwordx4 v[64:67], v[198:199], off
	global_load_dwordx4 v[68:71], v[200:201], off
	global_load_dwordx4 v[72:75], v[202:203], off
	global_load_dwordx4 v[76:79], v[204:205], off
	global_load_dwordx4 v[92:95], v[206:207], off
	global_load_dwordx4 v[128:131], v[208:209], off
	global_load_dwordx4 v[132:135], v[210:211], off
	global_load_dwordx4 v[136:139], v[212:213], off
	global_load_dwordx4 v[140:143], v[214:215], off
	global_load_dwordx4 v[144:147], v[216:217], off
	global_load_dwordx4 v[148:151], v[218:219], off
	global_load_dwordx4 v[152:155], v[220:221], off
	global_load_dwordx4 v[156:159], v[222:223], off
	v_add_u32_e32 v243, v232, v226
	v_add_u32_e32 v244, v233, v227
	v_bfrev_b32_e32 v80, 1
	v_mov_b32_e32 v81, v80
	v_mov_b32_e32 v82, v80
	v_mov_b32_e32 v83, v80
	v_mov_b32_e32 v84, v80
	v_mov_b32_e32 v85, v80
	v_mov_b32_e32 v86, v80
	v_mov_b32_e32 v87, v80
	v_mov_b32_e32 v88, v80
	v_mov_b32_e32 v89, v80
	v_mov_b32_e32 v90, v80
	v_mov_b32_e32 v91, v80
	s_cmp_ge_i32 s22, s77
	s_waitcnt vmcnt(23)
	ds_write_b128 v242, v[2:5] offset:8704
	s_waitcnt vmcnt(22)
	ds_write_b128 v242, v[6:9] offset:8736
	s_waitcnt vmcnt(21)
	ds_write_b128 v242, v[10:13] offset:8768
	s_waitcnt vmcnt(20)
	ds_write_b128 v242, v[32:35] offset:8800
	s_waitcnt vmcnt(19)
	ds_write_b128 v242, v[36:39] offset:13312
	s_waitcnt vmcnt(18)
	ds_write_b128 v242, v[40:43] offset:13344
	s_waitcnt vmcnt(17)
	ds_write_b128 v242, v[44:47] offset:13376
	s_waitcnt vmcnt(16)
	ds_write_b128 v242, v[48:51] offset:13408
	s_waitcnt vmcnt(15)
	ds_write_b128 v243, v[52:55]
	s_waitcnt vmcnt(14)
	ds_write_b128 v244, v[56:59] offset:4608
	s_waitcnt vmcnt(13)
	ds_write_b128 v243, v[60:63] offset:1152
	s_waitcnt vmcnt(12)
	ds_write_b128 v244, v[64:67] offset:5120
	s_waitcnt vmcnt(11)
	ds_write_b128 v243, v[68:71] offset:2304
	s_waitcnt vmcnt(10)
	ds_write_b128 v244, v[72:75] offset:5632
	s_waitcnt vmcnt(9)
	ds_write_b128 v243, v[76:79] offset:3456
	s_waitcnt vmcnt(8)
	ds_write_b128 v244, v[92:95] offset:6144
	s_waitcnt lgkmcnt(0)
	ds_read_b128 v[48:51], v242
	ds_read_b128 v[2:5], v242 offset:8704
	v_mov_b32_e32 v92, v80
	v_mov_b32_e32 v93, v80
	v_mov_b32_e32 v94, v80
	v_mov_b32_e32 v95, v80
	v_mov_b64_e32 v[32:33], v[80:81]
	v_mov_b64_e32 v[34:35], v[82:83]
	v_mov_b64_e32 v[36:37], v[84:85]
	v_mov_b64_e32 v[38:39], v[86:87]
	v_mov_b64_e32 v[40:41], v[88:89]
	v_mov_b64_e32 v[42:43], v[90:91]
	v_mov_b64_e32 v[44:45], v[92:93]
	v_mov_b64_e32 v[46:47], v[94:95]
	ds_read_b128 v[52:55], v242 offset:32
	ds_read_b128 v[6:9], v242 offset:8736
	s_waitcnt lgkmcnt(2)
	v_mfma_f32_32x32x16_bf16 v[32:47], v[48:51], v[2:5], v[32:47]
	s_waitcnt lgkmcnt(0)
	v_mfma_f32_32x32x16_bf16 v[32:47], v[52:55], v[6:9], v[32:47]
	ds_read_b128 v[56:59], v242 offset:64
	ds_read_b128 v[2:5], v242 offset:8768
	ds_read_b128 v[60:63], v242 offset:96
	ds_read_b128 v[6:9], v242 offset:8800
	s_waitcnt lgkmcnt(2)
	v_mfma_f32_32x32x16_bf16 v[32:47], v[56:59], v[2:5], v[32:47]
	s_waitcnt lgkmcnt(0)
	v_mfma_f32_32x32x16_bf16 v[32:47], v[60:63], v[6:9], v[32:47]
	s_cbranch_scc1 .LBB0_1918
	ds_read_b128 v[64:67], v242 offset:13312
	ds_read_b128 v[68:71], v242 offset:13344
	v_mov_b32_e32 v14, v0
	v_mov_b32_e32 v15, v0
	v_mov_b32_e32 v1, v0
	v_mov_b32_e32 v2, v0
	v_mov_b32_e32 v3, v0
	v_mov_b32_e32 v4, v0
	v_mov_b32_e32 v5, v0
	v_mov_b32_e32 v6, v0
	v_mov_b32_e32 v7, v0
	v_mov_b32_e32 v8, v0
	v_mov_b32_e32 v9, v0
	v_mov_b32_e32 v10, v0
	v_mov_b32_e32 v11, v0
	v_mov_b32_e32 v12, v0
	v_mov_b32_e32 v13, v0
	v_mov_b64_e32 v[94:95], v[14:15]
	v_mov_b64_e32 v[92:93], v[12:13]
	v_mov_b64_e32 v[90:91], v[10:11]
	v_mov_b64_e32 v[88:89], v[8:9]
	v_mov_b64_e32 v[86:87], v[6:7]
	v_mov_b64_e32 v[84:85], v[4:5]
	v_mov_b64_e32 v[82:83], v[2:3]
	v_mov_b64_e32 v[80:81], v[0:1]
	ds_read_b128 v[2:5], v242 offset:13376
	ds_read_b128 v[6:9], v242 offset:13408
	s_waitcnt lgkmcnt(3)
	v_mfma_f32_32x32x16_bf16 v[80:95], v[48:51], v[64:67], v[80:95]
	s_waitcnt lgkmcnt(2)
	v_mfma_f32_32x32x16_bf16 v[80:95], v[52:55], v[68:71], v[80:95]
	s_waitcnt lgkmcnt(1)
	v_mfma_f32_32x32x16_bf16 v[80:95], v[56:59], v[2:5], v[80:95]
	s_waitcnt lgkmcnt(0)
	v_mfma_f32_32x32x16_bf16 v[80:95], v[60:63], v[6:9], v[80:95]
